# combo3 + R3 retention-output PV blocks: the four V^T LDS reads issued together with counted waits
# speedup vs baseline: 1.0116x; 1.0019x over previous
.LBB0_174:
	s_and_b32 s14, s81, 3
	s_lshl_b32 s74, s14, 2
	v_mov_b32_e32 v18, s74
	global_load_dword v2, v18, s[82:83]
	global_load_dword v193, v18, s[96:97]
	s_mov_b32 s84, 0x3fb8aa3b
	s_mov_b32 s2, 0xc2ce8ed0
	s_mov_b32 s93, 0x42b17218
	s_mov_b32 s16, 0x3f2aaaab
	s_mov_b32 s17, 0x3f317218
	s_mov_b32 s18, 0x33800000
	s_and_b32 s15, s3, 0xffffff80
	v_lshl_add_u64 v[20:21], v[46:47], 0, v[44:45]
	v_add_u32_e32 v24, s15, v83
	v_ashrrev_i32_e32 v25, 31, v24
	v_lshlrev_b64 v[28:29], 9, v[24:25]
	v_add_u32_e32 v188, 0x9000, v176
	s_add_i32 s81, s81, s80
	s_add_i32 s3, s3, s63
	s_waitcnt vmcnt(1)
	v_mul_f32_e32 v3, 0x3fb8aa3b, v2
	v_fma_f32 v4, v2, s84, -v3
	v_rndne_f32_e32 v5, v3
	v_fmac_f32_e32 v4, 0x32a5705f, v2
	v_sub_f32_e32 v3, v3, v5
	v_add_f32_e32 v3, v3, v4
	v_exp_f32_e32 v3, v3
	v_cvt_i32_f32_e32 v4, v5
	v_cmp_ngt_f32_e32 vcc, s2, v2
	v_ldexp_f32 v3, v3, v4
	s_nop 0
	v_cndmask_b32_e32 v3, 0, v3, vcc
	v_cmp_nlt_f32_e32 vcc, s93, v2
	s_nop 1
	v_cndmask_b32_e32 v19, v245, v3, vcc
	v_sub_f32_e32 v4, 1.0, v19
	v_add_f32_e32 v2, -1.0, v4
	v_sub_f32_e32 v3, v2, v4
	v_add_f32_e32 v3, 1.0, v3
	v_sub_f32_e64 v2, -v19, v2
	v_add_f32_e32 v5, v2, v3
	v_frexp_mant_f32_e32 v2, v4
	v_cmp_gt_f32_e32 vcc, s16, v2
	v_cvt_f64_f32_e32 v[2:3], v4
	v_frexp_exp_i32_f64_e32 v2, v[2:3]
	v_subbrev_co_u32_e32 v10, vcc, 0, v2, vcc
	v_sub_u32_e32 v2, 0, v10
	v_ldexp_f32 v3, v4, v2
	v_add_f32_e32 v4, -1.0, v3
	v_add_f32_e32 v6, 1.0, v3
	v_ldexp_f32 v2, v5, v2
	v_add_f32_e32 v5, 1.0, v4
	v_add_f32_e32 v7, -1.0, v6
	v_sub_f32_e32 v5, v3, v5
	v_sub_f32_e32 v3, v3, v7
	v_add_f32_e32 v5, v2, v5
	v_add_f32_e32 v2, v2, v3
	v_add_f32_e32 v11, v6, v2
	v_rcp_f32_e32 v13, v11
	v_sub_f32_e32 v3, v11, v6
	v_sub_f32_e32 v12, v2, v3
	v_add_f32_e32 v3, v4, v5
	v_mul_f32_e32 v15, v3, v13
	v_sub_f32_e32 v2, v3, v4
	v_mul_f32_e32 v4, v11, v15
	v_fma_f32 v6, v15, v11, -v4
	v_fmac_f32_e32 v6, v15, v12
	v_sub_f32_e32 v14, v5, v2
	v_add_f32_e32 v2, v4, v6
	v_sub_f32_e32 v5, v3, v2
	v_pk_add_f32 v[8:9], v[2:3], v[4:5] neg_lo:[0,1] neg_hi:[0,1]
	v_mov_b32_e32 v7, v2
	v_pk_add_f32 v[2:3], v[8:9], v[6:7] neg_lo:[0,1] neg_hi:[0,1]
	v_cmp_nlt_f32_e32 vcc, 1.0, v19
	v_add_f32_e32 v3, v14, v3
	v_add_f32_e32 v2, v2, v3
	v_add_f32_e32 v3, v5, v2
	v_mul_f32_e32 v14, v13, v3
	v_mul_f32_e32 v4, v11, v14
	v_fma_f32 v6, v14, v11, -v4
	v_fmac_f32_e32 v6, v14, v12
	v_sub_f32_e32 v5, v5, v3
	v_add_f32_e32 v11, v2, v5
	v_add_f32_e32 v2, v4, v6
	v_sub_f32_e32 v5, v3, v2
	v_pk_add_f32 v[8:9], v[2:3], v[4:5] neg_lo:[0,1] neg_hi:[0,1]
	v_mov_b32_e32 v7, v2
	v_pk_add_f32 v[2:3], v[8:9], v[6:7] neg_lo:[0,1] neg_hi:[0,1]
	v_cmp_lt_f32_e64 s[74:75], |v19|, s18
	v_add_f32_e32 v3, v11, v3
	v_add_f32_e32 v2, v2, v3
	v_add_f32_e32 v3, v15, v14
	v_add_f32_e32 v2, v5, v2
	v_sub_f32_e32 v4, v3, v15
	v_mul_f32_e32 v2, v13, v2
	v_sub_f32_e32 v4, v14, v4
	v_add_f32_e32 v4, v4, v2
	v_add_f32_e32 v6, v3, v4
	v_mul_f32_e32 v7, v6, v6
	v_fmamk_f32 v2, v7, 0x3e9b6dac, v237
	v_fmaak_f32 v191, v7, v2, 0x3f2aaada
	v_cvt_f32_i32_e32 v2, v10
	v_sub_f32_e32 v3, v6, v3
	v_sub_f32_e32 v3, v4, v3
	v_ldexp_f32 v8, v3, 1
	v_mul_f32_e32 v3, v6, v7
	v_ldexp_f32 v5, v6, 1
	v_pk_mul_f32 v[6:7], v[2:3], v[190:191]
	s_nop 0
	v_fma_f32 v4, v2, s17, -v6
	v_fmac_f32_e32 v4, 0xb102e308, v2
	v_pk_add_f32 v[2:3], v[6:7], v[4:5]
	s_nop 0
	v_sub_f32_e32 v5, v3, v5
	v_sub_f32_e32 v5, v7, v5
	v_add_f32_e32 v9, v8, v5
	v_mov_b32_e32 v8, v6
	v_pk_add_f32 v[6:7], v[2:3], v[6:7] neg_lo:[0,1] neg_hi:[0,1]
	v_pk_add_f32 v[10:11], v[2:3], v[8:9]
	v_mov_b32_e32 v5, v2
	v_mov_b32_e32 v7, v11
	v_pk_add_f32 v[12:13], v[4:5], v[6:7] neg_lo:[0,1] neg_hi:[0,1]
	v_pk_add_f32 v[4:5], v[4:5], v[6:7]
	v_mov_b32_e32 v16, v3
	v_pk_add_f32 v[6:7], v[4:5], v[2:3] op_sel:[1,0] op_sel_hi:[0,1] neg_lo:[0,1] neg_hi:[0,1]
	v_pk_add_f32 v[14:15], v[10:11], v[6:7] op_sel_hi:[1,0] neg_lo:[0,1] neg_hi:[0,1]
	v_mov_b32_e32 v10, v11
	v_mov_b32_e32 v11, v5
	v_mov_b32_e32 v17, v6
	v_pk_add_f32 v[6:7], v[10:11], v[16:17] neg_lo:[0,1] neg_hi:[0,1]
	v_mov_b32_e32 v8, v9
	v_mov_b32_e32 v9, v2
	v_pk_add_f32 v[2:3], v[8:9], v[6:7] neg_lo:[0,1] neg_hi:[0,1]
	v_mov_b32_e32 v14, v12
	v_pk_add_f32 v[6:7], v[14:15], v[2:3]
	v_mov_b32_e32 v13, v5
	v_pk_add_f32 v[8:9], v[6:7], v[6:7] op_sel:[0,1] op_sel_hi:[1,0]
	s_nop 0
	v_pk_add_f32 v[4:5], v[4:5], v[8:9] op_sel:[1,0] op_sel_hi:[0,1]
	v_mov_b32_e32 v7, v4
	v_pk_add_f32 v[10:11], v[6:7], v[12:13] neg_lo:[0,1] neg_hi:[0,1]
	v_mov_b32_e32 v3, v8
	v_sub_f32_e32 v5, v6, v10
	v_pk_add_f32 v[2:3], v[2:3], v[10:11] neg_lo:[0,1] neg_hi:[0,1]
	v_sub_f32_e32 v5, v12, v5
	v_add_f32_e32 v2, v2, v5
	v_add_f32_e32 v2, v2, v3
	v_add_f32_e32 v2, v4, v2
	v_cndmask_b32_e32 v2, v241, v2, vcc
	v_cmp_neq_f32_e32 vcc, 1.0, v19
	s_nop 1
	v_cndmask_b32_e32 v2, v238, v2, vcc
	v_cndmask_b32_e64 v15, v2, -v19, s[74:75]
	s_waitcnt vmcnt(0)
	v_mov_b32_e32 v2, v193
	v_mul_f32_e32 v3, 0x3fb8aa3b, v2
	v_fma_f32 v4, v2, s84, -v3
	v_rndne_f32_e32 v5, v3
	v_fmac_f32_e32 v4, 0x32a5705f, v2
	v_sub_f32_e32 v3, v3, v5
	v_add_f32_e32 v3, v3, v4
	v_exp_f32_e32 v3, v3
	v_cvt_i32_f32_e32 v4, v5
	v_cmp_ngt_f32_e32 vcc, s2, v2
	s_lshl_b32 s84, s14, 7
	s_mov_b32 s2, 0x1c804000
	v_ldexp_f32 v3, v3, v4
	v_cndmask_b32_e32 v3, 0, v3, vcc
	v_cmp_nlt_f32_e32 vcc, s93, v2
	s_nop 1
	v_cndmask_b32_e32 v14, v245, v3, vcc
	v_sub_f32_e32 v4, 1.0, v14
	v_add_f32_e32 v2, -1.0, v4
	v_sub_f32_e32 v3, v2, v4
	v_add_f32_e32 v3, 1.0, v3
	v_sub_f32_e64 v2, -v14, v2
	v_add_f32_e32 v5, v2, v3
	v_frexp_mant_f32_e32 v2, v4
	v_cmp_gt_f32_e32 vcc, s16, v2
	v_cvt_f64_f32_e32 v[2:3], v4
	v_frexp_exp_i32_f64_e32 v2, v[2:3]
	v_subbrev_co_u32_e32 v10, vcc, 0, v2, vcc
	v_sub_u32_e32 v2, 0, v10
	v_ldexp_f32 v3, v4, v2
	v_add_f32_e32 v4, -1.0, v3
	v_add_f32_e32 v6, 1.0, v3
	v_ldexp_f32 v2, v5, v2
	v_add_f32_e32 v5, 1.0, v4
	v_add_f32_e32 v7, -1.0, v6
	v_sub_f32_e32 v5, v3, v5
	v_sub_f32_e32 v3, v3, v7
	v_add_f32_e32 v5, v2, v5
	v_add_f32_e32 v2, v2, v3
	v_add_f32_e32 v11, v6, v2
	v_rcp_f32_e32 v13, v11
	v_sub_f32_e32 v3, v11, v6
	v_sub_f32_e32 v12, v2, v3
	v_add_f32_e32 v3, v4, v5
	v_mul_f32_e32 v17, v3, v13
	v_sub_f32_e32 v2, v3, v4
	v_mul_f32_e32 v4, v11, v17
	v_fma_f32 v6, v17, v11, -v4
	v_fmac_f32_e32 v6, v17, v12
	v_sub_f32_e32 v16, v5, v2
	v_add_f32_e32 v2, v4, v6
	v_sub_f32_e32 v5, v3, v2
	v_pk_add_f32 v[8:9], v[2:3], v[4:5] neg_lo:[0,1] neg_hi:[0,1]
	v_mov_b32_e32 v7, v2
	v_pk_add_f32 v[2:3], v[8:9], v[6:7] neg_lo:[0,1] neg_hi:[0,1]
	v_cmp_nlt_f32_e32 vcc, 1.0, v14
	v_add_f32_e32 v3, v16, v3
	v_add_f32_e32 v2, v2, v3
	v_add_f32_e32 v3, v5, v2
	v_mul_f32_e32 v16, v13, v3
	v_mul_f32_e32 v4, v11, v16
	v_fma_f32 v6, v16, v11, -v4
	v_fmac_f32_e32 v6, v16, v12
	v_sub_f32_e32 v5, v5, v3
	v_add_f32_e32 v11, v2, v5
	v_add_f32_e32 v2, v4, v6
	v_sub_f32_e32 v5, v3, v2
	v_pk_add_f32 v[8:9], v[2:3], v[4:5] neg_lo:[0,1] neg_hi:[0,1]
	v_mov_b32_e32 v7, v2
	v_pk_add_f32 v[2:3], v[8:9], v[6:7] neg_lo:[0,1] neg_hi:[0,1]
	v_cmp_lt_f32_e64 s[74:75], |v14|, s18
	v_add_f32_e32 v3, v11, v3
	v_add_f32_e32 v2, v2, v3
	v_add_f32_e32 v3, v17, v16
	v_add_f32_e32 v2, v5, v2
	v_sub_f32_e32 v4, v3, v17
	v_mul_f32_e32 v2, v13, v2
	v_sub_f32_e32 v4, v16, v4
	v_add_f32_e32 v4, v4, v2
	v_add_f32_e32 v6, v3, v4
	v_mul_f32_e32 v7, v6, v6
	v_fmamk_f32 v2, v7, 0x3e9b6dac, v237
	v_fmaak_f32 v191, v7, v2, 0x3f2aaada
	v_cvt_f32_i32_e32 v2, v10
	v_sub_f32_e32 v3, v6, v3
	v_sub_f32_e32 v3, v4, v3
	v_ldexp_f32 v8, v3, 1
	v_mul_f32_e32 v3, v6, v7
	v_ldexp_f32 v5, v6, 1
	v_pk_mul_f32 v[6:7], v[2:3], v[190:191]
	s_nop 0
	v_fma_f32 v4, v2, s17, -v6
	v_fmac_f32_e32 v4, 0xb102e308, v2
	v_pk_add_f32 v[2:3], v[6:7], v[4:5]
	v_readlane_b32 s16, v255, 30
	v_sub_f32_e32 v5, v3, v5
	v_sub_f32_e32 v5, v7, v5
	v_add_f32_e32 v9, v8, v5
	v_mov_b32_e32 v8, v6
	v_pk_add_f32 v[6:7], v[2:3], v[6:7] neg_lo:[0,1] neg_hi:[0,1]
	v_pk_add_f32 v[10:11], v[2:3], v[8:9]
	v_mov_b32_e32 v5, v2
	v_mov_b32_e32 v7, v11
	v_pk_add_f32 v[12:13], v[4:5], v[6:7] neg_lo:[0,1] neg_hi:[0,1]
	v_pk_add_f32 v[4:5], v[4:5], v[6:7]
	v_mov_b32_e32 v18, v3
	v_pk_add_f32 v[6:7], v[4:5], v[2:3] op_sel:[1,0] op_sel_hi:[0,1] neg_lo:[0,1] neg_hi:[0,1]
	v_pk_add_f32 v[16:17], v[10:11], v[6:7] op_sel_hi:[1,0] neg_lo:[0,1] neg_hi:[0,1]
	v_mov_b32_e32 v10, v11
	v_mov_b32_e32 v11, v5
	v_mov_b32_e32 v19, v6
	v_pk_add_f32 v[6:7], v[10:11], v[18:19] neg_lo:[0,1] neg_hi:[0,1]
	v_mov_b32_e32 v8, v9
	v_mov_b32_e32 v9, v2
	v_pk_add_f32 v[2:3], v[8:9], v[6:7] neg_lo:[0,1] neg_hi:[0,1]
	v_mov_b32_e32 v16, v12
	v_pk_add_f32 v[6:7], v[16:17], v[2:3]
	v_mov_b32_e32 v13, v5
	v_pk_add_f32 v[8:9], v[6:7], v[6:7] op_sel:[0,1] op_sel_hi:[1,0]
	v_readlane_b32 s17, v255, 31
	v_pk_add_f32 v[4:5], v[4:5], v[8:9] op_sel:[1,0] op_sel_hi:[0,1]
	v_mov_b32_e32 v7, v4
	v_pk_add_f32 v[10:11], v[6:7], v[12:13] neg_lo:[0,1] neg_hi:[0,1]
	v_mov_b32_e32 v3, v8
	v_sub_f32_e32 v5, v6, v10
	v_pk_add_f32 v[2:3], v[2:3], v[10:11] neg_lo:[0,1] neg_hi:[0,1]
	v_sub_f32_e32 v5, v12, v5
	v_add_f32_e32 v2, v2, v5
	v_add_f32_e32 v2, v2, v3
	v_add_f32_e32 v2, v4, v2
	v_cndmask_b32_e32 v2, v241, v2, vcc
	v_cmp_neq_f32_e32 vcc, 1.0, v14
	v_lshl_add_u64 v[12:13], v[30:31], 0, s[84:85]
	v_lshl_add_u64 v[10:11], v[32:33], 0, s[84:85]
	v_cndmask_b32_e32 v2, v238, v2, vcc
	v_cndmask_b32_e64 v14, v2, -v14, s[74:75]
	v_add_u32_e32 v2, s15, v82
	v_ashrrev_i32_e32 v3, 31, v2
	v_lshlrev_b64 v[6:7], 9, v[2:3]
	v_lshl_add_u64 v[2:3], v[12:13], 0, v[6:7]
	global_load_dwordx4 v[2:5], v[2:3], off
	v_lshl_add_u64 v[6:7], v[10:11], 0, v[6:7]
	global_load_dwordx4 v[6:9], v[6:7], off
	v_add_co_u32_e32 v16, vcc, s19, v20
	v_lshl_add_u64 v[12:13], v[12:13], 0, v[28:29]
	s_nop 0
	v_addc_co_u32_e32 v17, vcc, 0, v21, vcc
	v_add_co_u32_e32 v20, vcc, s2, v20
	v_lshl_add_u64 v[10:11], v[10:11], 0, v[28:29]
	s_nop 0
	v_addc_co_u32_e32 v21, vcc, 0, v21, vcc
	v_lshl_add_u64 v[28:29], v[46:47], 0, v[48:49]
	v_add_co_u32_e32 v50, vcc, s19, v28
	s_lshl_b32 s84, s14, 8
	s_nop 0
	v_addc_co_u32_e32 v51, vcc, 0, v29, vcc
	v_add_co_u32_e32 v28, vcc, s2, v28
	global_load_dwordx4 v[52:55], v[50:51], off
	s_nop 0
	v_addc_co_u32_e32 v29, vcc, 0, v29, vcc
	global_load_dwordx4 v[56:59], v[28:29], off
	v_or_b32_e32 v28, s15, v75
	v_ashrrev_i32_e32 v29, 31, v28
	v_lshlrev_b64 v[28:29], 10, v[28:29]
	v_lshl_add_u64 v[28:29], s[88:89], 0, v[28:29]
	v_lshl_add_u64 v[28:29], v[28:29], 0, s[84:85]
	global_load_dwordx4 v[16:19], v[16:17], off
	v_lshl_add_u64 v[60:61], v[36:37], 1, v[28:29]
	global_load_dwordx4 v[20:23], v[20:21], off
	v_lshl_add_u64 v[62:63], v[38:39], 1, v[28:29]
	global_load_dwordx4 v[24:27], v[12:13], off
	v_lshl_add_u64 v[64:65], v[40:41], 1, v[28:29]
	global_load_dwordx4 v[10:13], v[10:11], off
	s_waitcnt vmcnt(7)
	ds_write_b128 v84, v[2:5]
	s_waitcnt vmcnt(6)
	ds_write_b128 v84, v[6:9] offset:18432
	v_lshl_add_u64 v[28:29], v[42:43], 1, v[28:29]
	global_load_dwordx4 v[2:5], v[60:61], off
	global_load_dwordx4 v[6:9], v[62:63], off
	s_nop 0
	global_load_dwordx4 v[60:63], v[64:65], off
	s_nop 0
	global_load_dwordx4 v[64:67], v[28:29], off
	s_waitcnt vmcnt(7)
	ds_write_b128 v85, v[16:19]
	s_waitcnt vmcnt(6)
	ds_write_b128 v86, v[20:23]
	s_waitcnt vmcnt(5)
	ds_write_b128 v87, v[24:27]
	s_waitcnt vmcnt(4)
	ds_write_b128 v87, v[10:13] offset:18432
	ds_write_b128 v88, v[52:55]
	ds_write_b128 v89, v[56:59]
	s_waitcnt vmcnt(3)
	ds_write_b16 v90, v2 offset:36864
	ds_write_b16_d16_hi v90, v2 offset:37136
	ds_write_b16 v90, v3 offset:37408
	ds_write_b16_d16_hi v90, v3 offset:37680
	ds_write_b16 v90, v4 offset:37952
	ds_write_b16_d16_hi v90, v4 offset:38224
	ds_write_b16 v90, v5 offset:38496
	ds_write_b16_d16_hi v90, v5 offset:38768
	s_waitcnt vmcnt(2)
	ds_write_b16 v91, v6 offset:36864
	ds_write_b16_d16_hi v91, v6 offset:37136
	ds_write_b16 v91, v7 offset:37408
	ds_write_b16_d16_hi v91, v7 offset:37680
	ds_write_b16 v91, v8 offset:37952
	ds_write_b16_d16_hi v91, v8 offset:38224
	ds_write_b16 v91, v9 offset:38496
	ds_write_b16_d16_hi v91, v9 offset:38768
	s_waitcnt vmcnt(1)
	ds_write_b16 v92, v60 offset:36864
	ds_write_b16_d16_hi v92, v60 offset:37136
	ds_write_b16 v92, v61 offset:37408
	ds_write_b16_d16_hi v92, v61 offset:37680
	ds_write_b16 v92, v62 offset:37952
	ds_write_b16_d16_hi v92, v62 offset:38224
	ds_write_b16 v92, v63 offset:38496
	ds_write_b16_d16_hi v92, v63 offset:38768
	s_waitcnt vmcnt(0)
	ds_write_b16 v93, v64 offset:36864
	ds_write_b16_d16_hi v93, v64 offset:37136
	ds_write_b16 v93, v65 offset:37408
	ds_write_b16_d16_hi v93, v65 offset:37680
	ds_write_b16 v93, v66 offset:37952
	ds_write_b16_d16_hi v93, v66 offset:38224
	ds_write_b16 v93, v67 offset:38496
	ds_write_b16_d16_hi v93, v67 offset:38768
	v_add_u32_e32 v242, s15, v77
	v_ashrrev_i32_e32 v243, 31, v242
	v_lshlrev_b64 v[242:243], 10, v[242:243]
	v_lshl_add_u64 v[242:243], s[72:73], 0, v[242:243]
	v_lshl_add_u64 v[242:243], v[242:243], 0, s[84:85]
	v_lshl_add_u64 v[242:243], v[242:243], 0, v[0:1]
	global_load_dwordx2 v[206:207], v[242:243], off
	global_load_dwordx2 v[208:209], v[242:243], off offset:32
	global_load_dwordx2 v[210:211], v[242:243], off offset:64
	global_load_dwordx2 v[212:213], v[242:243], off offset:96
	global_load_dwordx2 v[214:215], v[242:243], off offset:128
	global_load_dwordx2 v[216:217], v[242:243], off offset:160
	global_load_dwordx2 v[218:219], v[242:243], off offset:192
	global_load_dwordx2 v[220:221], v[242:243], off offset:224
	s_waitcnt lgkmcnt(0)
	s_barrier
	ds_read_b128 v[6:9], v182
	ds_read_b128 v[2:5], v182 offset:64
	ds_read_b128 v[10:13], v183 offset:18432
	v_mul_f32_e32 v50, 0x3fb8aa3b, v15
	v_mul_f32_e32 v51, 0x3fb8aa3b, v14
	ds_read_b128 v[14:17], v183 offset:18496
	s_waitcnt lgkmcnt(1)
	v_mfma_f32_16x16x32_bf16 v[10:13], v[10:13], v[6:9], 0
	v_readlane_b32 s74, v255, 20
	v_readlane_b32 s75, v255, 21
	ds_read_b128 v[18:21], v183 offset:20800
	s_waitcnt lgkmcnt(1)
	v_mfma_f32_16x16x32_bf16 v[10:13], v[14:17], v[2:5], v[10:13]
	v_mul_f32_e32 v14, v51, v94
	v_mul_f32_e32 v15, v50, v95
	v_cndmask_b32_e64 v14, v15, v14, s[74:75]
	v_readlane_b32 s74, v255, 22
	v_mul_f32_e32 v15, v50, v97
	v_mul_f32_e32 v16, v51, v96
	v_readlane_b32 s75, v255, 23
	v_exp_f32_e32 v14, v14
	ds_read_b128 v[22:25], v183 offset:23104
	v_cndmask_b32_e64 v15, v15, v16, s[74:75]
	v_exp_f32_e32 v15, v15
	v_readlane_b32 s74, v255, 24
	v_readlane_b32 s75, v255, 25
	v_mul_f32_e32 v16, v51, v100
	v_pk_mul_f32 v[10:11], v[10:11], v[14:15]
	v_mul_f32_e32 v14, v50, v99
	v_mul_f32_e32 v15, v51, v98
	v_cndmask_b32_e64 v14, v14, v15, s[74:75]
	v_readlane_b32 s74, v255, 26
	v_mul_f32_e32 v15, v50, v101
	v_readlane_b32 s75, v255, 27
	v_exp_f32_e32 v14, v14
	ds_read_b128 v[26:29], v183 offset:25408
	v_cndmask_b32_e64 v15, v15, v16, s[74:75]
	v_exp_f32_e32 v15, v15
	v_readlane_b32 s74, v255, 28
	v_readlane_b32 s75, v255, 29
	ds_read_b128 v[52:55], v183 offset:27712
	v_pk_mul_f32 v[12:13], v[12:13], v[14:15]
	ds_read_b128 v[14:17], v183 offset:20736
	s_waitcnt lgkmcnt(0)
	v_mfma_f32_16x16x32_bf16 v[14:17], v[14:17], v[6:9], 0
	ds_read_b128 v[56:59], v183 offset:30016
	v_cvt_pk_bf16_f32 v10, v10, v11
	v_cvt_pk_bf16_f32 v11, v12, v13
	v_mfma_f32_16x16x32_bf16 v[14:17], v[18:21], v[2:5], v[14:17]
	v_mul_f32_e32 v18, v50, v103
	v_mul_f32_e32 v19, v51, v102
	v_cndmask_b32_e64 v18, v18, v19, s[74:75]
	v_mul_f32_e32 v19, v50, v105
	v_mul_f32_e32 v20, v51, v104
	v_cndmask_b32_e64 v19, v19, v20, s[16:17]
	v_exp_f32_e32 v18, v18
	v_exp_f32_e32 v19, v19
	v_readlane_b32 s16, v255, 32
	v_readlane_b32 s17, v255, 33
	v_mul_f32_e32 v20, v51, v108
	v_pk_mul_f32 v[14:15], v[18:19], v[14:15]
	v_mul_f32_e32 v18, v50, v107
	v_mul_f32_e32 v19, v51, v106
	v_cndmask_b32_e64 v18, v18, v19, s[16:17]
	v_mul_f32_e32 v19, v50, v109
	v_cndmask_b32_e64 v19, v19, v20, s[20:21]
	v_exp_f32_e32 v18, v18
	v_exp_f32_e32 v19, v19
	v_cvt_pk_bf16_f32 v12, v14, v15
	s_mov_b32 s74, 0xf800000
	v_lshl_add_u64 v[46:47], v[46:47], 0, s[76:77]
	v_pk_mul_f32 v[16:17], v[18:19], v[16:17]
	ds_read_b128 v[18:21], v183 offset:23040
	s_waitcnt lgkmcnt(0)
	v_mfma_f32_16x16x32_bf16 v[18:21], v[18:21], v[6:9], 0
	v_cvt_pk_bf16_f32 v13, v16, v17
	v_mfma_f32_16x16x32_bf16 v[18:21], v[22:25], v[2:5], v[18:21]
	v_mul_f32_e32 v22, v50, v111
	v_mul_f32_e32 v23, v51, v110
	v_cndmask_b32_e64 v22, v22, v23, s[22:23]
	v_mul_f32_e32 v23, v50, v113
	v_mul_f32_e32 v24, v51, v112
	v_cndmask_b32_e64 v23, v23, v24, s[24:25]
	v_exp_f32_e32 v22, v22
	v_exp_f32_e32 v23, v23
	v_mul_f32_e32 v24, v51, v116
	v_pk_mul_f32 v[18:19], v[22:23], v[18:19]
	v_mul_f32_e32 v22, v50, v115
	v_mul_f32_e32 v23, v51, v114
	v_cndmask_b32_e64 v22, v22, v23, s[26:27]
	v_mul_f32_e32 v23, v50, v117
	v_cndmask_b32_e64 v23, v23, v24, s[28:29]
	v_exp_f32_e32 v22, v22
	v_exp_f32_e32 v23, v23
	v_cvt_pk_bf16_f32 v14, v18, v19
	v_pk_mul_f32 v[20:21], v[22:23], v[20:21]
	ds_read_b128 v[22:25], v183 offset:25344
	s_waitcnt lgkmcnt(0)
	v_mfma_f32_16x16x32_bf16 v[22:25], v[22:25], v[6:9], 0
	v_cvt_pk_bf16_f32 v15, v20, v21
	v_mfma_f32_16x16x32_bf16 v[22:25], v[26:29], v[2:5], v[22:25]
	v_mul_f32_e32 v26, v50, v119
	v_mul_f32_e32 v27, v51, v118
	v_cndmask_b32_e64 v26, v26, v27, s[30:31]
	v_mul_f32_e32 v27, v50, v121
	v_mul_f32_e32 v28, v51, v120
	v_cndmask_b32_e64 v27, v27, v28, s[34:35]
	v_exp_f32_e32 v26, v26
	v_exp_f32_e32 v27, v27
	v_mul_f32_e32 v28, v51, v124
	v_pk_mul_f32 v[22:23], v[26:27], v[22:23]
	v_mul_f32_e32 v26, v50, v123
	v_mul_f32_e32 v27, v51, v122
	v_cndmask_b32_e64 v26, v26, v27, s[36:37]
	v_mul_f32_e32 v27, v50, v125
	v_cndmask_b32_e64 v27, v27, v28, s[38:39]
	v_exp_f32_e32 v26, v26
	v_exp_f32_e32 v27, v27
	v_cvt_pk_bf16_f32 v16, v22, v23
	v_pk_mul_f32 v[24:25], v[26:27], v[24:25]
	ds_read_b128 v[26:29], v183 offset:27648
	s_waitcnt lgkmcnt(0)
	v_mfma_f32_16x16x32_bf16 v[26:29], v[26:29], v[6:9], 0
	v_cvt_pk_bf16_f32 v17, v24, v25
	v_mfma_f32_16x16x32_bf16 v[26:29], v[52:55], v[2:5], v[26:29]
	v_mul_f32_e32 v52, v50, v127
	v_mul_f32_e32 v53, v51, v126
	v_cndmask_b32_e64 v52, v52, v53, s[40:41]
	v_mul_f32_e32 v53, v50, v129
	v_mul_f32_e32 v54, v51, v128
	v_cndmask_b32_e64 v53, v53, v54, s[42:43]
	v_exp_f32_e32 v52, v52
	v_exp_f32_e32 v53, v53
	v_mul_f32_e32 v54, v51, v132
	v_pk_mul_f32 v[26:27], v[52:53], v[26:27]
	v_mul_f32_e32 v52, v50, v131
	v_mul_f32_e32 v53, v51, v130
	v_cndmask_b32_e64 v52, v52, v53, s[44:45]
	v_mul_f32_e32 v53, v50, v133
	v_cndmask_b32_e64 v53, v53, v54, s[46:47]
	v_exp_f32_e32 v52, v52
	v_exp_f32_e32 v53, v53
	v_cvt_pk_bf16_f32 v18, v26, v27
	v_mul_f32_e32 v26, v50, v78
	v_exp_f32_e32 v74, v26
	v_pk_mul_f32 v[28:29], v[52:53], v[28:29]
	ds_read_b128 v[52:55], v183 offset:29952
	s_waitcnt lgkmcnt(0)
	v_mfma_f32_16x16x32_bf16 v[52:55], v[52:55], v[6:9], 0
	v_mul_f32_e32 v26, v51, v79
	v_cvt_pk_bf16_f32 v19, v28, v29
	v_exp_f32_e32 v76, v26
	v_mfma_f32_16x16x32_bf16 v[52:55], v[56:59], v[2:5], v[52:55]
	v_mul_f32_e32 v56, v50, v135
	v_mul_f32_e32 v57, v51, v134
	v_cndmask_b32_e64 v56, v56, v57, s[48:49]
	v_mul_f32_e32 v57, v50, v137
	v_mul_f32_e32 v58, v51, v136
	v_cndmask_b32_e64 v57, v57, v58, s[50:51]
	v_exp_f32_e32 v56, v56
	v_exp_f32_e32 v57, v57
	s_nop 0
	v_pk_mul_f32 v[60:61], v[56:57], v[52:53]
	v_mul_f32_e32 v52, v50, v139
	v_mul_f32_e32 v53, v51, v138
	v_cndmask_b32_e64 v52, v52, v53, s[52:53]
	v_mul_f32_e32 v53, v50, v141
	v_mul_f32_e32 v56, v51, v140
	v_cndmask_b32_e64 v53, v53, v56, s[54:55]
	v_exp_f32_e32 v52, v52
	v_exp_f32_e32 v53, v53
	ds_read_b128 v[56:59], v183 offset:32320
	v_cvt_pk_bf16_f32 v20, v60, v61
	v_pk_mul_f32 v[62:63], v[52:53], v[54:55]
	ds_read_b128 v[52:55], v183 offset:32256
	s_waitcnt lgkmcnt(0)
	v_mfma_f32_16x16x32_bf16 v[52:55], v[52:55], v[6:9], 0
	v_cvt_pk_bf16_f32 v21, v62, v63
	v_mfma_f32_16x16x32_bf16 v[52:55], v[56:59], v[2:5], v[52:55]
	v_mul_f32_e32 v56, v50, v143
	v_mul_f32_e32 v57, v51, v142
	v_cndmask_b32_e64 v56, v56, v57, s[6:7]
	v_mul_f32_e32 v57, v50, v145
	v_mul_f32_e32 v58, v51, v144
	v_cndmask_b32_e64 v57, v57, v58, s[8:9]
	v_exp_f32_e32 v56, v56
	v_exp_f32_e32 v57, v57
	s_nop 0
	v_pk_mul_f32 v[64:65], v[56:57], v[52:53]
	v_mul_f32_e32 v52, v50, v147
	v_mul_f32_e32 v53, v51, v146
	v_cndmask_b32_e64 v52, v52, v53, s[10:11]
	v_mul_f32_e32 v53, v50, v149
	v_mul_f32_e32 v56, v51, v148
	v_cndmask_b32_e64 v53, v53, v56, s[12:13]
	v_exp_f32_e32 v52, v52
	v_exp_f32_e32 v53, v53
	ds_read_b128 v[56:59], v183 offset:34624
	v_cvt_pk_bf16_f32 v22, v64, v65
	v_pk_mul_f32 v[66:67], v[52:53], v[54:55]
	ds_read_b128 v[52:55], v183 offset:34560
	s_waitcnt lgkmcnt(0)
	v_mfma_f32_16x16x32_bf16 v[52:55], v[52:55], v[6:9], 0
	v_cvt_pk_bf16_f32 v23, v66, v67
	v_mfma_f32_16x16x32_bf16 v[52:55], v[56:59], v[2:5], v[52:55]
	v_mul_f32_e32 v56, v50, v151
	v_mul_f32_e32 v57, v51, v150
	v_cndmask_b32_e64 v56, v56, v57, s[64:65]
	v_mul_f32_e32 v57, v50, v153
	v_mul_f32_e32 v58, v51, v152
	v_cndmask_b32_e64 v57, v57, v58, s[66:67]
	v_exp_f32_e32 v56, v56
	v_exp_f32_e32 v57, v57
	v_mul_f32_e32 v58, v51, v156
	v_pk_mul_f32 v[52:53], v[56:57], v[52:53]
	v_mul_f32_e32 v56, v50, v155
	v_mul_f32_e32 v57, v51, v154
	v_cndmask_b32_e64 v56, v56, v57, s[68:69]
	v_mul_f32_e32 v57, v50, v157
	v_cndmask_b32_e64 v57, v57, v58, s[70:71]
	v_exp_f32_e32 v56, v56
	v_exp_f32_e32 v57, v57
	v_cvt_pk_bf16_f32 v24, v52, v53
	v_pk_mul_f32 v[54:55], v[56:57], v[54:55]
	s_nop 0
	v_cvt_pk_bf16_f32 v25, v54, v55
	v_add_u32_e32 v54, 0x9000, v158
	ds_read2_b64 v[26:29], v54 offset1:4
	ds_read2_b64 v[50:53], v54 offset0:8 offset1:12
	ds_read2_b64 v[224:227], v54 offset0:16 offset1:20
	ds_read2_b64 v[246:249], v54 offset0:24 offset1:28
	s_waitcnt lgkmcnt(3)
	v_mfma_f32_16x16x32_bf16 v[26:29], v[26:29], v[10:13], 0
	s_waitcnt lgkmcnt(2)
	v_mfma_f32_16x16x32_bf16 v[26:29], v[50:53], v[14:17], v[26:29]
	s_waitcnt lgkmcnt(1)
	v_mfma_f32_16x16x32_bf16 v[26:29], v[224:227], v[18:21], v[26:29]
	s_waitcnt lgkmcnt(0)
	v_mfma_f32_16x16x32_bf16 v[26:29], v[246:249], v[22:25], v[26:29]
	ds_read_b128 v[50:53], v159
	ds_read_b128 v[54:57], v160
	ds_read_b128 v[58:61], v159 offset:64
	ds_read_b128 v[62:65], v160 offset:64
	s_waitcnt lgkmcnt(3)
	v_mfma_f32_16x16x32_bf16 v[50:53], v[50:53], v[6:9], 0
	s_waitcnt lgkmcnt(2)
	v_mfma_f32_16x16x32_bf16 v[54:57], v[54:57], v[6:9], 0
	s_waitcnt lgkmcnt(1)
	v_mfma_f32_16x16x32_bf16 v[50:53], v[58:61], v[2:5], v[50:53]
	s_waitcnt lgkmcnt(0)
	v_mfma_f32_16x16x32_bf16 v[54:57], v[62:65], v[2:5], v[54:57]
	s_nop 5
	v_fma_f32 v26, v74, v50, v26
	v_fma_f32 v27, v74, v51, v27
	v_pk_fma_f32 v[28:29], v[74:75], v[52:53], v[28:29] op_sel_hi:[0,1,1]
	v_pk_fma_f32 v[72:73], v[76:77], v[54:55], v[26:27] op_sel_hi:[0,1,1]
	v_add_u32_e32 v54, 0x9000, v161
	v_pk_fma_f32 v[70:71], v[76:77], v[56:57], v[28:29] op_sel_hi:[0,1,1]
	ds_read2_b64 v[26:29], v54 offset1:4
	ds_read2_b64 v[50:53], v54 offset0:8 offset1:12
	ds_read2_b64 v[224:227], v54 offset0:16 offset1:20
	ds_read2_b64 v[246:249], v54 offset0:24 offset1:28
	s_waitcnt lgkmcnt(3)
	v_mfma_f32_16x16x32_bf16 v[26:29], v[26:29], v[10:13], 0
	s_waitcnt lgkmcnt(2)
	v_mfma_f32_16x16x32_bf16 v[26:29], v[50:53], v[14:17], v[26:29]
	s_waitcnt lgkmcnt(1)
	v_mfma_f32_16x16x32_bf16 v[26:29], v[224:227], v[18:21], v[26:29]
	s_waitcnt lgkmcnt(0)
	v_mfma_f32_16x16x32_bf16 v[26:29], v[246:249], v[22:25], v[26:29]
	ds_read_b128 v[50:53], v162
	ds_read_b128 v[54:57], v163
	ds_read_b128 v[58:61], v162 offset:64
	ds_read_b128 v[62:65], v163 offset:64
	s_waitcnt lgkmcnt(3)
	v_mfma_f32_16x16x32_bf16 v[50:53], v[50:53], v[6:9], 0
	s_waitcnt lgkmcnt(2)
	v_mfma_f32_16x16x32_bf16 v[54:57], v[54:57], v[6:9], 0
	s_waitcnt lgkmcnt(1)
	v_mfma_f32_16x16x32_bf16 v[50:53], v[58:61], v[2:5], v[50:53]
	s_waitcnt lgkmcnt(0)
	v_mfma_f32_16x16x32_bf16 v[54:57], v[62:65], v[2:5], v[54:57]
	s_nop 5
	v_fma_f32 v26, v74, v50, v26
	v_fma_f32 v27, v74, v51, v27
	v_pk_fma_f32 v[28:29], v[74:75], v[52:53], v[28:29] op_sel_hi:[0,1,1]
	v_pk_fma_f32 v[68:69], v[76:77], v[54:55], v[26:27] op_sel_hi:[0,1,1]
	v_add_u32_e32 v54, 0x9000, v164
	v_pk_fma_f32 v[66:67], v[76:77], v[56:57], v[28:29] op_sel_hi:[0,1,1]
	ds_read2_b64 v[26:29], v54 offset1:4
	ds_read2_b64 v[50:53], v54 offset0:8 offset1:12
	ds_read2_b64 v[224:227], v54 offset0:16 offset1:20
	ds_read2_b64 v[246:249], v54 offset0:24 offset1:28
	s_waitcnt lgkmcnt(3)
	v_mfma_f32_16x16x32_bf16 v[26:29], v[26:29], v[10:13], 0
	s_waitcnt lgkmcnt(2)
	v_mfma_f32_16x16x32_bf16 v[26:29], v[50:53], v[14:17], v[26:29]
	s_waitcnt lgkmcnt(1)
	v_mfma_f32_16x16x32_bf16 v[26:29], v[224:227], v[18:21], v[26:29]
	s_waitcnt lgkmcnt(0)
	v_mfma_f32_16x16x32_bf16 v[26:29], v[246:249], v[22:25], v[26:29]
	ds_read_b128 v[50:53], v165
	ds_read_b128 v[54:57], v166
	ds_read_b128 v[58:61], v165 offset:64
	ds_read_b128 v[62:65], v166 offset:64
	s_waitcnt lgkmcnt(3)
	v_mfma_f32_16x16x32_bf16 v[50:53], v[50:53], v[6:9], 0
	s_waitcnt lgkmcnt(2)
	v_mfma_f32_16x16x32_bf16 v[54:57], v[54:57], v[6:9], 0
	s_waitcnt lgkmcnt(1)
	v_mfma_f32_16x16x32_bf16 v[50:53], v[58:61], v[2:5], v[50:53]
	s_waitcnt lgkmcnt(0)
	v_mfma_f32_16x16x32_bf16 v[54:57], v[62:65], v[2:5], v[54:57]
	s_nop 5
	v_fma_f32 v26, v74, v50, v26
	v_fma_f32 v27, v74, v51, v27
	v_pk_fma_f32 v[28:29], v[74:75], v[52:53], v[28:29] op_sel_hi:[0,1,1]
	v_pk_fma_f32 v[64:65], v[76:77], v[54:55], v[26:27] op_sel_hi:[0,1,1]
	v_add_u32_e32 v54, 0x9000, v167
	v_pk_fma_f32 v[62:63], v[76:77], v[56:57], v[28:29] op_sel_hi:[0,1,1]
	ds_read2_b64 v[26:29], v54 offset1:4
	ds_read2_b64 v[50:53], v54 offset0:8 offset1:12
	ds_read2_b64 v[224:227], v54 offset0:16 offset1:20
	ds_read2_b64 v[246:249], v54 offset0:24 offset1:28
	s_waitcnt lgkmcnt(3)
	v_mfma_f32_16x16x32_bf16 v[26:29], v[26:29], v[10:13], 0
	s_waitcnt lgkmcnt(2)
	v_mfma_f32_16x16x32_bf16 v[26:29], v[50:53], v[14:17], v[26:29]
	s_waitcnt lgkmcnt(1)
	v_mfma_f32_16x16x32_bf16 v[26:29], v[224:227], v[18:21], v[26:29]
	s_waitcnt lgkmcnt(0)
	v_mfma_f32_16x16x32_bf16 v[26:29], v[246:249], v[22:25], v[26:29]
	ds_read_b128 v[50:53], v168
	ds_read_b128 v[54:57], v169
	ds_read_b128 v[58:61], v168 offset:64
	ds_read_b128 v[184:187], v169 offset:64
	s_waitcnt lgkmcnt(3)
	v_mfma_f32_16x16x32_bf16 v[50:53], v[50:53], v[6:9], 0
	s_waitcnt lgkmcnt(2)
	v_mfma_f32_16x16x32_bf16 v[54:57], v[54:57], v[6:9], 0
	s_waitcnt lgkmcnt(1)
	v_mfma_f32_16x16x32_bf16 v[50:53], v[58:61], v[2:5], v[50:53]
	s_waitcnt lgkmcnt(0)
	v_mfma_f32_16x16x32_bf16 v[54:57], v[184:187], v[2:5], v[54:57]
	s_nop 5
	v_fma_f32 v26, v74, v50, v26
	v_fma_f32 v27, v74, v51, v27
	v_pk_fma_f32 v[28:29], v[74:75], v[52:53], v[28:29] op_sel_hi:[0,1,1]
	v_pk_fma_f32 v[60:61], v[76:77], v[54:55], v[26:27] op_sel_hi:[0,1,1]
	v_add_u32_e32 v54, 0x9000, v170
	v_pk_fma_f32 v[58:59], v[76:77], v[56:57], v[28:29] op_sel_hi:[0,1,1]
	ds_read2_b64 v[26:29], v54 offset1:4
	ds_read2_b64 v[50:53], v54 offset0:8 offset1:12
	ds_read2_b64 v[224:227], v54 offset0:16 offset1:20
	ds_read2_b64 v[246:249], v54 offset0:24 offset1:28
	s_waitcnt lgkmcnt(3)
	v_mfma_f32_16x16x32_bf16 v[26:29], v[26:29], v[10:13], 0
	s_waitcnt lgkmcnt(2)
	v_mfma_f32_16x16x32_bf16 v[26:29], v[50:53], v[14:17], v[26:29]
	s_waitcnt lgkmcnt(1)
	v_mfma_f32_16x16x32_bf16 v[26:29], v[224:227], v[18:21], v[26:29]
	s_waitcnt lgkmcnt(0)
	v_mfma_f32_16x16x32_bf16 v[26:29], v[246:249], v[22:25], v[26:29]
	ds_read_b128 v[50:53], v171
	ds_read_b128 v[54:57], v172
	ds_read_b128 v[184:187], v171 offset:64
	ds_read_b128 v[194:197], v172 offset:64
	s_waitcnt lgkmcnt(3)
	v_mfma_f32_16x16x32_bf16 v[50:53], v[50:53], v[6:9], 0
	s_waitcnt lgkmcnt(2)
	v_mfma_f32_16x16x32_bf16 v[54:57], v[54:57], v[6:9], 0
	s_waitcnt lgkmcnt(1)
	v_mfma_f32_16x16x32_bf16 v[50:53], v[184:187], v[2:5], v[50:53]
	s_waitcnt lgkmcnt(0)
	v_mfma_f32_16x16x32_bf16 v[184:187], v[194:197], v[2:5], v[54:57]
	s_nop 5
	v_fma_f32 v26, v74, v50, v26
	v_fma_f32 v27, v74, v51, v27
	v_pk_fma_f32 v[28:29], v[74:75], v[52:53], v[28:29] op_sel_hi:[0,1,1]
	v_pk_fma_f32 v[56:57], v[76:77], v[184:185], v[26:27] op_sel_hi:[0,1,1]
	v_add_u32_e32 v184, 0x9000, v173
	v_pk_fma_f32 v[54:55], v[76:77], v[186:187], v[28:29] op_sel_hi:[0,1,1]
	ds_read2_b64 v[26:29], v184 offset1:4
	ds_read2_b64 v[50:53], v184 offset0:8 offset1:12
	ds_read2_b64 v[224:227], v184 offset0:16 offset1:20
	ds_read2_b64 v[246:249], v184 offset0:24 offset1:28
	s_waitcnt lgkmcnt(3)
	v_mfma_f32_16x16x32_bf16 v[26:29], v[26:29], v[10:13], 0
	s_waitcnt lgkmcnt(2)
	v_mfma_f32_16x16x32_bf16 v[26:29], v[50:53], v[14:17], v[26:29]
	s_waitcnt lgkmcnt(1)
	v_mfma_f32_16x16x32_bf16 v[26:29], v[224:227], v[18:21], v[26:29]
	s_waitcnt lgkmcnt(0)
	v_mfma_f32_16x16x32_bf16 v[26:29], v[246:249], v[22:25], v[26:29]
	ds_read_b128 v[50:53], v174
	ds_read_b128 v[184:187], v175
	ds_read_b128 v[194:197], v174 offset:64
	ds_read_b128 v[198:201], v175 offset:64
	s_waitcnt lgkmcnt(3)
	v_mfma_f32_16x16x32_bf16 v[50:53], v[50:53], v[6:9], 0
	s_waitcnt lgkmcnt(2)
	v_mfma_f32_16x16x32_bf16 v[184:187], v[184:187], v[6:9], 0
	s_waitcnt lgkmcnt(1)
	v_mfma_f32_16x16x32_bf16 v[50:53], v[194:197], v[2:5], v[50:53]
	s_waitcnt lgkmcnt(0)
	v_mfma_f32_16x16x32_bf16 v[184:187], v[198:201], v[2:5], v[184:187]
	s_nop 5
	v_fma_f32 v28, v74, v52, v28
	v_fma_f32 v29, v74, v53, v29
	v_pk_fma_f32 v[26:27], v[74:75], v[50:51], v[26:27] op_sel_hi:[0,1,1]
	v_pk_fma_f32 v[50:51], v[76:77], v[186:187], v[28:29] op_sel_hi:[0,1,1]
	v_pk_fma_f32 v[52:53], v[76:77], v[184:185], v[26:27] op_sel_hi:[0,1,1]
	ds_read2_b64 v[26:29], v188 offset1:4
	ds_read2_b64 v[184:187], v188 offset0:8 offset1:12
	s_waitcnt lgkmcnt(1)
	v_mfma_f32_16x16x32_bf16 v[26:29], v[26:29], v[10:13], 0
	s_waitcnt lgkmcnt(0)
	v_mfma_f32_16x16x32_bf16 v[26:29], v[184:187], v[14:17], v[26:29]
	ds_read2_b64 v[184:187], v188 offset0:16 offset1:20
	s_waitcnt lgkmcnt(0)
	v_mfma_f32_16x16x32_bf16 v[26:29], v[184:187], v[18:21], v[26:29]
	ds_read2_b64 v[184:187], v188 offset0:24 offset1:28
	v_add_u32_e32 v188, 0x9000, v179
	s_waitcnt lgkmcnt(0)
	v_mfma_f32_16x16x32_bf16 v[26:29], v[184:187], v[22:25], v[26:29]
	ds_read_b128 v[184:187], v177
	ds_read_b128 v[194:197], v178
	ds_read_b128 v[198:201], v177 offset:64
	ds_read_b128 v[202:205], v178 offset:64
	s_waitcnt lgkmcnt(3)
	v_mfma_f32_16x16x32_bf16 v[184:187], v[184:187], v[6:9], 0
	s_waitcnt lgkmcnt(2)
	v_mfma_f32_16x16x32_bf16 v[194:197], v[194:197], v[6:9], 0
	s_waitcnt lgkmcnt(1)
	v_mfma_f32_16x16x32_bf16 v[184:187], v[198:201], v[2:5], v[184:187]
	s_waitcnt lgkmcnt(0)
	v_mfma_f32_16x16x32_bf16 v[194:197], v[202:205], v[2:5], v[194:197]
	s_nop 5
	v_fma_f32 v28, v74, v186, v28
	v_fma_f32 v29, v74, v187, v29
	v_pk_fma_f32 v[184:185], v[74:75], v[184:185], v[26:27] op_sel_hi:[0,1,1]
	v_pk_fma_f32 v[26:27], v[76:77], v[196:197], v[28:29] op_sel_hi:[0,1,1]
	v_pk_fma_f32 v[28:29], v[76:77], v[194:195], v[184:185] op_sel_hi:[0,1,1]
	ds_read2_b64 v[184:187], v188 offset1:4
	s_waitcnt lgkmcnt(0)
	v_mfma_f32_16x16x32_bf16 v[10:13], v[184:187], v[10:13], 0
	ds_read2_b64 v[184:187], v188 offset0:8 offset1:12
	s_waitcnt lgkmcnt(0)
	v_mfma_f32_16x16x32_bf16 v[10:13], v[184:187], v[14:17], v[10:13]
	ds_read2_b64 v[14:17], v188 offset0:16 offset1:20
	s_waitcnt lgkmcnt(0)
	v_mfma_f32_16x16x32_bf16 v[10:13], v[14:17], v[18:21], v[10:13]
	ds_read2_b64 v[14:17], v188 offset0:24 offset1:28
	s_waitcnt lgkmcnt(0)
	v_mfma_f32_16x16x32_bf16 v[10:13], v[14:17], v[22:25], v[10:13]
	ds_read_b128 v[14:17], v180
	ds_read_b128 v[18:21], v181
	s_waitcnt lgkmcnt(1)
	v_mfma_f32_16x16x32_bf16 v[14:17], v[14:17], v[6:9], 0
	s_waitcnt lgkmcnt(0)
	v_mfma_f32_16x16x32_bf16 v[6:9], v[18:21], v[6:9], 0
	ds_read_b128 v[18:21], v180 offset:64
	ds_read_b128 v[22:25], v181 offset:64
	s_waitcnt lgkmcnt(1)
	v_mfma_f32_16x16x32_bf16 v[14:17], v[18:21], v[2:5], v[14:17]
	s_waitcnt lgkmcnt(0)
	v_mfma_f32_16x16x32_bf16 v[4:7], v[22:25], v[2:5], v[6:9]
	v_mov_b32_e32 v232, s14
	v_mov_b32_e32 v233, 0
	v_lshlrev_b32_e32 v232, 9, v232
	v_lshl_add_u64 v[232:233], v[34:35], 0, v[232:233]
	global_load_dwordx4 v[22:25], v[232:233], off
	global_load_dwordx4 v[184:187], v[232:233], off offset:64
	global_load_dwordx4 v[194:197], v[232:233], off offset:128
	global_load_dwordx4 v[198:201], v[232:233], off offset:192
	global_load_dwordx4 v[202:205], v[232:233], off offset:256
	global_load_dwordx4 v[224:227], v[232:233], off offset:320
	global_load_dwordx4 v[246:249], v[232:233], off offset:384
	global_load_dwordx4 v[250:253], v[232:233], off offset:448
	s_nop 5
	v_fma_f32 v2, v74, v16, v12
	v_fma_f32 v3, v74, v17, v13
	v_add_f32_e32 v12, v58, v59
	v_mov_b32_e32 v13, v55
	v_pk_fma_f32 v[8:9], v[74:75], v[14:15], v[10:11] op_sel_hi:[0,1,1]
	v_mov_b32_e32 v10, v71
	v_pk_fma_f32 v[2:3], v[76:77], v[6:7], v[2:3] op_sel_hi:[0,1,1]
	v_pk_fma_f32 v[4:5], v[76:77], v[4:5], v[8:9] op_sel_hi:[0,1,1]
	v_mov_b32_e32 v6, v72
	v_mov_b32_e32 v7, v68
	v_mov_b32_e32 v8, v73
	v_mov_b32_e32 v9, v69
	v_pk_add_f32 v[6:7], v[6:7], v[8:9]
	v_mov_b32_e32 v8, v70
	v_mov_b32_e32 v9, v66
	v_mov_b32_e32 v11, v67
	v_pk_add_f32 v[8:9], v[8:9], v[10:11]
	v_mov_b32_e32 v10, v64
	v_pk_add_f32 v[6:7], v[6:7], v[8:9]
	v_pk_mov_b32 v[8:9], v[64:65], v[62:63] op_sel:[1,0]
	v_mov_b32_e32 v11, v63
	v_pk_add_f32 v[8:9], v[8:9], v[10:11]
	v_add_f32_e32 v6, 0, v6
	v_pk_add_f32 v[8:9], v[8:9], v[8:9] op_sel:[0,1] op_sel_hi:[1,0]
	v_add_f32_e32 v6, v6, v7
	v_add_f32_e32 v10, v60, v61
	v_mov_b32_e32 v7, v56
	v_mov_b32_e32 v9, v57
	v_mov_b32_e32 v11, v54
	v_pk_add_f32 v[6:7], v[6:7], v[8:9]
	v_pk_add_f32 v[8:9], v[10:11], v[12:13]
	v_mov_b32_e32 v10, v52
	v_pk_add_f32 v[6:7], v[6:7], v[8:9]
	v_pk_mov_b32 v[8:9], v[52:53], v[50:51] op_sel:[1,0]
	v_mov_b32_e32 v11, v51
	v_pk_add_f32 v[8:9], v[8:9], v[10:11]
	v_pk_add_f32 v[6:7], v[6:7], v[6:7] op_sel:[0,1] op_sel_hi:[1,0]
	v_pk_add_f32 v[8:9], v[8:9], v[8:9] op_sel:[0,1] op_sel_hi:[1,0]
	v_add_f32_e32 v10, v28, v29
	v_add_f32_e32 v12, v26, v27
	v_mov_b32_e32 v7, v4
	v_mov_b32_e32 v9, v5
	v_mov_b32_e32 v11, v2
	v_mov_b32_e32 v13, v3
	v_pk_add_f32 v[6:7], v[6:7], v[8:9]
	v_pk_add_f32 v[8:9], v[10:11], v[12:13]
	s_nop 0
	v_pk_add_f32 v[6:7], v[6:7], v[8:9]
	s_nop 0
	v_add_f32_e32 v6, v6, v7
	ds_bpermute_b32 v7, v80, v6
	s_waitcnt lgkmcnt(0)
	v_add_f32_e32 v6, v6, v7
	ds_bpermute_b32 v7, v81, v6
	s_waitcnt lgkmcnt(0)
	v_add_f32_e32 v14, v6, v7
	v_fmamk_f32 v73, v14, 0xbc000000, v73
	v_fmamk_f32 v69, v14, 0xbc000000, v69
	v_fmamk_f32 v71, v14, 0xbc000000, v71
	v_fmac_f32_e32 v72, 0xbc000000, v14
	v_fmamk_f32 v67, v14, 0xbc000000, v67
	v_fmac_f32_e32 v68, 0xbc000000, v14
	v_mov_b32_e32 v8, v73
	v_mov_b32_e32 v9, v69
	v_fmac_f32_e32 v70, 0xbc000000, v14
	v_fmac_f32_e32 v66, 0xbc000000, v14
	v_mov_b32_e32 v6, v72
	v_mov_b32_e32 v7, v68
	v_pk_mul_f32 v[8:9], v[8:9], v[8:9]
	v_mov_b32_e32 v10, v71
	v_mov_b32_e32 v11, v67
	v_pk_fma_f32 v[6:7], v[6:7], v[6:7], v[8:9]
	v_mov_b32_e32 v8, v70
	v_mov_b32_e32 v9, v66
	v_pk_mul_f32 v[10:11], v[10:11], v[10:11]
	v_fmamk_f32 v65, v14, 0xbc000000, v65
	v_pk_fma_f32 v[8:9], v[8:9], v[8:9], v[10:11]
	v_fmac_f32_e32 v64, 0xbc000000, v14
	v_pk_add_f32 v[6:7], v[6:7], v[8:9]
	v_fmamk_f32 v63, v14, 0xbc000000, v63
	v_fmac_f32_e32 v62, 0xbc000000, v14
	v_pk_add_f32 v[6:7], v[6:7], v[6:7] op_sel_hi:[0,1]
	v_pk_mul_f32 v[8:9], v[62:63], v[62:63]
	v_pk_mul_f32 v[10:11], v[64:65], v[64:65]
	v_fmac_f32_e32 v60, 0xbc000000, v14
	v_pk_mov_b32 v[12:13], v[10:11], v[8:9] op_sel:[1,0]
	v_mov_b32_e32 v11, v9
	v_fmamk_f32 v61, v14, 0xbc000000, v61
	v_fmac_f32_e32 v58, 0xbc000000, v14
	v_mul_f32_e32 v6, v60, v60
	v_pk_add_f32 v[8:9], v[12:13], v[10:11]
	v_fmamk_f32 v59, v14, 0xbc000000, v59
	v_pk_fma_f32 v[10:11], v[60:61], v[60:61], v[6:7] op_sel_hi:[1,1,0]
	v_mul_f32_e32 v6, v58, v58
	v_pk_add_f32 v[8:9], v[8:9], v[8:9] op_sel_hi:[0,1]
	v_pk_fma_f32 v[12:13], v[58:59], v[58:59], v[6:7] op_sel_hi:[1,1,0]
	v_fmamk_f32 v55, v14, 0xbc000000, v55
	v_fmac_f32_e32 v54, 0xbc000000, v14
	v_fmamk_f32 v57, v14, 0xbc000000, v57
	v_fmac_f32_e32 v56, 0xbc000000, v14
	v_mul_f32_e32 v10, v56, v56
	v_mul_f32_e32 v12, v57, v57
	v_mul_f32_e32 v8, v54, v54
	v_mul_f32_e32 v6, v55, v55
	v_pk_add_f32 v[10:11], v[10:11], v[12:13]
	v_pk_add_f32 v[6:7], v[8:9], v[6:7]
	v_fmamk_f32 v53, v14, 0xbc000000, v53
	v_pk_add_f32 v[6:7], v[10:11], v[6:7]
	v_fmac_f32_e32 v52, 0xbc000000, v14
	v_fmamk_f32 v51, v14, 0xbc000000, v51
	v_fmac_f32_e32 v50, 0xbc000000, v14
	v_pk_add_f32 v[6:7], v[6:7], v[6:7] op_sel_hi:[0,1]
	v_pk_mul_f32 v[8:9], v[50:51], v[50:51]
	v_pk_mul_f32 v[10:11], v[52:53], v[52:53]
	v_fmac_f32_e32 v28, 0xbc000000, v14
	v_pk_mov_b32 v[12:13], v[10:11], v[8:9] op_sel:[1,0]
	v_mov_b32_e32 v11, v9
	v_fmamk_f32 v29, v14, 0xbc000000, v29
	v_fmac_f32_e32 v26, 0xbc000000, v14
	v_mul_f32_e32 v6, v28, v28
	v_pk_add_f32 v[8:9], v[12:13], v[10:11]
	v_fmamk_f32 v27, v14, 0xbc000000, v27
	v_pk_fma_f32 v[10:11], v[28:29], v[28:29], v[6:7] op_sel_hi:[1,1,0]
	v_mul_f32_e32 v6, v26, v26
	v_pk_add_f32 v[8:9], v[8:9], v[8:9] op_sel_hi:[0,1]
	v_pk_fma_f32 v[12:13], v[26:27], v[26:27], v[6:7] op_sel_hi:[1,1,0]
	v_fmamk_f32 v3, v14, 0xbc000000, v3
	v_fmac_f32_e32 v2, 0xbc000000, v14
	v_fmamk_f32 v5, v14, 0xbc000000, v5
	v_fmac_f32_e32 v4, 0xbc000000, v14
	v_mul_f32_e32 v10, v4, v4
	v_mul_f32_e32 v12, v5, v5
	v_mul_f32_e32 v8, v2, v2
	v_mul_f32_e32 v6, v3, v3
	v_pk_add_f32 v[10:11], v[10:11], v[12:13]
	v_pk_add_f32 v[6:7], v[8:9], v[6:7]
	s_nop 0
	v_pk_add_f32 v[6:7], v[10:11], v[6:7]
	s_nop 0
	v_add_f32_e32 v6, v6, v7
	ds_bpermute_b32 v7, v80, v6
	s_waitcnt lgkmcnt(0)
	v_add_f32_e32 v6, v6, v7
	ds_bpermute_b32 v7, v81, v6
	s_waitcnt lgkmcnt(0)
	v_add_f32_e32 v6, v6, v7
	v_fmamk_f32 v6, v6, 0x3c000000, v223
	v_cmp_gt_f32_e32 vcc, s74, v6
	v_mul_f32_e32 v7, 0x4f800000, v6
	s_nop 0
	v_cndmask_b32_e32 v6, v6, v7, vcc
	v_sqrt_f32_e32 v7, v6
	s_nop 0
	v_add_u32_e32 v8, -1, v7
	v_fma_f32 v9, -v8, v7, v6
	v_cmp_ge_f32_e64 s[74:75], 0, v9
	v_add_u32_e32 v9, 1, v7
	s_nop 0
	v_cndmask_b32_e64 v8, v7, v8, s[74:75]
	v_fma_f32 v7, -v9, v7, v6
	v_cmp_lt_f32_e64 s[74:75], 0, v7
	s_nop 1
	v_cndmask_b32_e64 v7, v8, v9, s[74:75]
	v_mul_f32_e32 v8, 0x37800000, v7
	v_cndmask_b32_e32 v7, v7, v8, vcc
	v_mov_b32_e32 v8, 0x260
	v_cmp_class_f32_e32 vcc, v6, v8
	s_nop 1
	v_cndmask_b32_e32 v6, v7, v6, vcc
	v_div_scale_f32 v7, s[74:75], v6, v6, 1.0
	v_rcp_f32_e32 v8, v7
	s_nop 0
	v_fma_f32 v9, -v7, v8, 1.0
	v_fmac_f32_e32 v8, v9, v8
	v_div_scale_f32 v9, vcc, 1.0, v6, 1.0
	v_mul_f32_e32 v10, v9, v8
	v_fma_f32 v11, -v7, v10, v9
	v_fmac_f32_e32 v10, v11, v8
	v_fma_f32 v7, -v7, v10, v9
	v_div_fmas_f32 v7, v7, v8, v10
	v_add_u32_e32 v8, s15, v77
	v_ashrrev_i32_e32 v9, 31, v8
	v_lshlrev_b64 v[8:9], 10, v[8:9]
	v_lshl_add_u64 v[8:9], s[72:73], 0, v[8:9]
	v_lshl_add_u64 v[8:9], v[8:9], 0, s[84:85]
	v_lshl_add_u64 v[8:9], v[8:9], 0, v[0:1]
	s_lshl_b32 s84, s14, 9
	v_lshl_add_u64 v[10:11], v[34:35], 0, s[84:85]
	s_waitcnt vmcnt(0)
	v_mov_b64_e32 v[16:17], v[206:207]
	v_mov_b64_e32 v[12:13], v[22:23]
	v_mov_b64_e32 v[14:15], v[24:25]
	v_div_fixup_f32 v6, v7, v6, 1.0
	v_pk_mul_f32 v[18:19], v[72:73], v[6:7] op_sel_hi:[1,0]
	v_pk_mul_f32 v[20:21], v[70:71], v[6:7] op_sel_hi:[1,0]
	s_cmpk_lt_i32 s81, 0x600
	v_pk_mul_f32 v[12:13], v[12:13], v[18:19]
	v_lshlrev_b32_e32 v18, 16, v16
	v_mul_f32_e32 v7, 0xbfb8aa3b, v18
	v_exp_f32_e32 v7, v7
	v_and_b32_e32 v19, 0xffff0000, v16
	v_pk_mul_f32 v[14:15], v[14:15], v[20:21]
	v_lshlrev_b32_e32 v16, 16, v17
	v_add_f32_e32 v7, 1.0, v7
	v_rcp_f32_e32 v20, v7
	v_mul_f32_e32 v7, 0xbfb8aa3b, v19
	v_exp_f32_e32 v7, v7
	v_and_b32_e32 v17, 0xffff0000, v17
	v_add_f32_e32 v7, 1.0, v7
	v_rcp_f32_e32 v21, v7
	v_mul_f32_e32 v7, 0xbfb8aa3b, v16
	v_exp_f32_e32 v7, v7
	v_pk_mul_f32 v[18:19], v[20:21], v[18:19]
	s_nop 0
	v_pk_mul_f32 v[12:13], v[18:19], v[12:13]
	v_add_f32_e32 v7, 1.0, v7
	v_rcp_f32_e32 v18, v7
	v_mul_f32_e32 v7, 0xbfb8aa3b, v17
	v_exp_f32_e32 v7, v7
	v_cvt_pk_bf16_f32 v12, v12, v13
	v_add_f32_e32 v7, 1.0, v7
	v_rcp_f32_e32 v19, v7
	v_pk_mul_f32 v[20:21], v[66:67], v[6:7] op_sel_hi:[1,0]
	v_pk_mul_f32 v[16:17], v[18:19], v[16:17]
	s_nop 0
	v_pk_mul_f32 v[14:15], v[16:17], v[14:15]
	v_pk_mul_f32 v[18:19], v[68:69], v[6:7] op_sel_hi:[1,0]
	v_cvt_pk_bf16_f32 v13, v14, v15
	global_store_dwordx2 v[8:9], v[12:13], off
	v_mov_b64_e32 v[16:17], v[208:209]
	v_mov_b64_e32 v[12:13], v[184:185]
	v_mov_b64_e32 v[14:15], v[186:187]
	v_pk_mul_f32 v[12:13], v[12:13], v[18:19]
	v_lshlrev_b32_e32 v18, 16, v16
	v_mul_f32_e32 v7, 0xbfb8aa3b, v18
	v_exp_f32_e32 v7, v7
	v_and_b32_e32 v19, 0xffff0000, v16
	v_pk_mul_f32 v[14:15], v[14:15], v[20:21]
	v_lshlrev_b32_e32 v16, 16, v17
	v_add_f32_e32 v7, 1.0, v7
	v_rcp_f32_e32 v20, v7
	v_mul_f32_e32 v7, 0xbfb8aa3b, v19
	v_exp_f32_e32 v7, v7
	v_and_b32_e32 v17, 0xffff0000, v17
	v_add_f32_e32 v7, 1.0, v7
	v_rcp_f32_e32 v21, v7
	v_mul_f32_e32 v7, 0xbfb8aa3b, v16
	v_exp_f32_e32 v7, v7
	v_pk_mul_f32 v[18:19], v[20:21], v[18:19]
	s_nop 0
	v_pk_mul_f32 v[12:13], v[18:19], v[12:13]
	v_add_f32_e32 v7, 1.0, v7
	v_rcp_f32_e32 v18, v7
	v_mul_f32_e32 v7, 0xbfb8aa3b, v17
	v_exp_f32_e32 v7, v7
	v_cvt_pk_bf16_f32 v12, v12, v13
	v_add_f32_e32 v7, 1.0, v7
	v_rcp_f32_e32 v19, v7
	v_pk_mul_f32 v[20:21], v[62:63], v[6:7] op_sel_hi:[1,0]
	v_pk_mul_f32 v[16:17], v[18:19], v[16:17]
	s_nop 0
	v_pk_mul_f32 v[14:15], v[16:17], v[14:15]
	v_pk_mul_f32 v[18:19], v[64:65], v[6:7] op_sel_hi:[1,0]
	v_cvt_pk_bf16_f32 v13, v14, v15
	global_store_dwordx2 v[8:9], v[12:13], off offset:32
	v_mov_b64_e32 v[16:17], v[210:211]
	v_mov_b64_e32 v[12:13], v[194:195]
	v_mov_b64_e32 v[14:15], v[196:197]
	v_pk_mul_f32 v[12:13], v[12:13], v[18:19]
	v_lshlrev_b32_e32 v18, 16, v16
	v_mul_f32_e32 v7, 0xbfb8aa3b, v18
	v_exp_f32_e32 v7, v7
	v_and_b32_e32 v19, 0xffff0000, v16
	v_pk_mul_f32 v[14:15], v[14:15], v[20:21]
	v_lshlrev_b32_e32 v16, 16, v17
	v_add_f32_e32 v7, 1.0, v7
	v_rcp_f32_e32 v20, v7
	v_mul_f32_e32 v7, 0xbfb8aa3b, v19
	v_exp_f32_e32 v7, v7
	v_and_b32_e32 v17, 0xffff0000, v17
	v_add_f32_e32 v7, 1.0, v7
	v_rcp_f32_e32 v21, v7
	v_mul_f32_e32 v7, 0xbfb8aa3b, v16
	v_exp_f32_e32 v7, v7
	v_pk_mul_f32 v[18:19], v[20:21], v[18:19]
	s_nop 0
	v_pk_mul_f32 v[12:13], v[18:19], v[12:13]
	v_add_f32_e32 v7, 1.0, v7
	v_rcp_f32_e32 v18, v7
	v_mul_f32_e32 v7, 0xbfb8aa3b, v17
	v_exp_f32_e32 v7, v7
	v_cvt_pk_bf16_f32 v12, v12, v13
	v_add_f32_e32 v7, 1.0, v7
	v_rcp_f32_e32 v19, v7
	v_pk_mul_f32 v[20:21], v[58:59], v[6:7] op_sel_hi:[1,0]
	v_pk_mul_f32 v[16:17], v[18:19], v[16:17]
	s_nop 0
	v_pk_mul_f32 v[14:15], v[16:17], v[14:15]
	v_pk_mul_f32 v[18:19], v[60:61], v[6:7] op_sel_hi:[1,0]
	v_cvt_pk_bf16_f32 v13, v14, v15
	global_store_dwordx2 v[8:9], v[12:13], off offset:64
	v_mov_b64_e32 v[12:13], v[212:213]
	v_mov_b64_e32 v[14:15], v[198:199]
	v_mov_b64_e32 v[16:17], v[200:201]
	v_pk_mul_f32 v[14:15], v[14:15], v[18:19]
	v_lshlrev_b32_e32 v18, 16, v12
	v_mul_f32_e32 v7, 0xbfb8aa3b, v18
	v_exp_f32_e32 v7, v7
	v_and_b32_e32 v19, 0xffff0000, v12
	v_pk_mul_f32 v[16:17], v[16:17], v[20:21]
	v_add_f32_e32 v7, 1.0, v7
	v_rcp_f32_e32 v20, v7
	v_mul_f32_e32 v7, 0xbfb8aa3b, v19
	v_exp_f32_e32 v7, v7
	s_nop 0
	v_add_f32_e32 v7, 1.0, v7
	v_rcp_f32_e32 v21, v7
	s_nop 0
	v_pk_mul_f32 v[18:19], v[20:21], v[18:19]
	s_nop 0
	v_pk_mul_f32 v[14:15], v[18:19], v[14:15]
	s_nop 0
	v_cvt_pk_bf16_f32 v12, v14, v15
	v_lshlrev_b32_e32 v14, 16, v13
	v_mul_f32_e32 v7, 0xbfb8aa3b, v14
	v_exp_f32_e32 v7, v7
	v_and_b32_e32 v15, 0xffff0000, v13
	v_add_f32_e32 v7, 1.0, v7
	v_rcp_f32_e32 v18, v7
	v_mul_f32_e32 v7, 0xbfb8aa3b, v15
	v_exp_f32_e32 v7, v7
	s_nop 0
	v_add_f32_e32 v7, 1.0, v7
	v_rcp_f32_e32 v19, v7
	v_pk_mul_f32 v[20:21], v[54:55], v[6:7] op_sel_hi:[1,0]
	v_pk_mul_f32 v[14:15], v[18:19], v[14:15]
	s_nop 0
	v_pk_mul_f32 v[14:15], v[14:15], v[16:17]
	v_pk_mul_f32 v[18:19], v[56:57], v[6:7] op_sel_hi:[1,0]
	v_cvt_pk_bf16_f32 v13, v14, v15
	global_store_dwordx2 v[8:9], v[12:13], off offset:96
	v_mov_b64_e32 v[16:17], v[214:215]
	v_mov_b64_e32 v[12:13], v[202:203]
	v_mov_b64_e32 v[14:15], v[204:205]
	v_pk_mul_f32 v[12:13], v[12:13], v[18:19]
	v_lshlrev_b32_e32 v18, 16, v16
	v_mul_f32_e32 v7, 0xbfb8aa3b, v18
	v_exp_f32_e32 v7, v7
	v_and_b32_e32 v19, 0xffff0000, v16
	v_pk_mul_f32 v[14:15], v[14:15], v[20:21]
	v_lshlrev_b32_e32 v16, 16, v17
	v_add_f32_e32 v7, 1.0, v7
	v_rcp_f32_e32 v20, v7
	v_mul_f32_e32 v7, 0xbfb8aa3b, v19
	v_exp_f32_e32 v7, v7
	v_and_b32_e32 v17, 0xffff0000, v17
	v_add_f32_e32 v7, 1.0, v7
	v_rcp_f32_e32 v21, v7
	v_mul_f32_e32 v7, 0xbfb8aa3b, v16
	v_exp_f32_e32 v7, v7
	v_pk_mul_f32 v[18:19], v[20:21], v[18:19]
	s_nop 0
	v_pk_mul_f32 v[12:13], v[18:19], v[12:13]
	v_add_f32_e32 v7, 1.0, v7
	v_rcp_f32_e32 v18, v7
	v_mul_f32_e32 v7, 0xbfb8aa3b, v17
	v_exp_f32_e32 v7, v7
	v_cvt_pk_bf16_f32 v12, v12, v13
	v_add_f32_e32 v7, 1.0, v7
	v_rcp_f32_e32 v19, v7
	v_pk_mul_f32 v[20:21], v[50:51], v[6:7] op_sel_hi:[1,0]
	v_pk_mul_f32 v[16:17], v[18:19], v[16:17]
	s_nop 0
	v_pk_mul_f32 v[14:15], v[16:17], v[14:15]
	v_pk_mul_f32 v[18:19], v[52:53], v[6:7] op_sel_hi:[1,0]
	v_cvt_pk_bf16_f32 v13, v14, v15
	global_store_dwordx2 v[8:9], v[12:13], off offset:128
	v_mov_b64_e32 v[16:17], v[216:217]
	v_mov_b64_e32 v[12:13], v[224:225]
	v_mov_b64_e32 v[14:15], v[226:227]
	v_pk_mul_f32 v[12:13], v[12:13], v[18:19]
	v_lshlrev_b32_e32 v18, 16, v16
	v_mul_f32_e32 v7, 0xbfb8aa3b, v18
	v_exp_f32_e32 v7, v7
	v_and_b32_e32 v19, 0xffff0000, v16
	v_pk_mul_f32 v[14:15], v[14:15], v[20:21]
	v_lshlrev_b32_e32 v16, 16, v17
	v_add_f32_e32 v7, 1.0, v7
	v_rcp_f32_e32 v20, v7
	v_mul_f32_e32 v7, 0xbfb8aa3b, v19
	v_exp_f32_e32 v7, v7
	v_and_b32_e32 v17, 0xffff0000, v17
	v_add_f32_e32 v7, 1.0, v7
	v_rcp_f32_e32 v21, v7
	v_mul_f32_e32 v7, 0xbfb8aa3b, v16
	v_exp_f32_e32 v7, v7
	v_pk_mul_f32 v[18:19], v[20:21], v[18:19]
	s_nop 0
	v_pk_mul_f32 v[12:13], v[18:19], v[12:13]
	v_add_f32_e32 v7, 1.0, v7
	v_rcp_f32_e32 v18, v7
	v_mul_f32_e32 v7, 0xbfb8aa3b, v17
	v_exp_f32_e32 v7, v7
	v_cvt_pk_bf16_f32 v12, v12, v13
	v_add_f32_e32 v7, 1.0, v7
	v_rcp_f32_e32 v19, v7
	v_pk_mul_f32 v[20:21], v[26:27], v[6:7] op_sel_hi:[1,0]
	v_pk_mul_f32 v[16:17], v[18:19], v[16:17]
	s_nop 0
	v_pk_mul_f32 v[14:15], v[16:17], v[14:15]
	v_pk_mul_f32 v[18:19], v[28:29], v[6:7] op_sel_hi:[1,0]
	v_cvt_pk_bf16_f32 v13, v14, v15
	global_store_dwordx2 v[8:9], v[12:13], off offset:160
	v_mov_b64_e32 v[16:17], v[218:219]
	v_mov_b64_e32 v[12:13], v[246:247]
	v_mov_b64_e32 v[14:15], v[248:249]
	v_pk_mul_f32 v[12:13], v[12:13], v[18:19]
	v_lshlrev_b32_e32 v18, 16, v16
	v_mul_f32_e32 v7, 0xbfb8aa3b, v18
	v_exp_f32_e32 v7, v7
	v_and_b32_e32 v19, 0xffff0000, v16
	v_pk_mul_f32 v[14:15], v[14:15], v[20:21]
	v_lshlrev_b32_e32 v16, 16, v17
	v_add_f32_e32 v7, 1.0, v7
	v_rcp_f32_e32 v20, v7
	v_mul_f32_e32 v7, 0xbfb8aa3b, v19
	v_exp_f32_e32 v7, v7
	v_and_b32_e32 v17, 0xffff0000, v17
	v_add_f32_e32 v7, 1.0, v7
	v_rcp_f32_e32 v21, v7
	v_mul_f32_e32 v7, 0xbfb8aa3b, v16
	v_exp_f32_e32 v7, v7
	v_pk_mul_f32 v[18:19], v[20:21], v[18:19]
	s_nop 0
	v_pk_mul_f32 v[12:13], v[18:19], v[12:13]
	v_add_f32_e32 v7, 1.0, v7
	v_rcp_f32_e32 v18, v7
	v_mul_f32_e32 v7, 0xbfb8aa3b, v17
	v_exp_f32_e32 v7, v7
	v_cvt_pk_bf16_f32 v12, v12, v13
	v_add_f32_e32 v7, 1.0, v7
	v_rcp_f32_e32 v19, v7
	v_pk_mul_f32 v[4:5], v[4:5], v[6:7] op_sel_hi:[1,0]
	v_pk_mul_f32 v[2:3], v[2:3], v[6:7] op_sel_hi:[1,0]
	v_pk_mul_f32 v[16:17], v[18:19], v[16:17]
	s_nop 0
	v_pk_mul_f32 v[14:15], v[16:17], v[14:15]
	s_nop 0
	v_cvt_pk_bf16_f32 v13, v14, v15
	global_store_dwordx2 v[8:9], v[12:13], off offset:192
	v_mov_b64_e32 v[12:13], v[220:221]
	v_mov_b64_e32 v[14:15], v[250:251]
	v_mov_b64_e32 v[16:17], v[252:253]
	v_lshlrev_b32_e32 v6, 16, v12
	v_and_b32_e32 v7, 0xffff0000, v12
	v_mul_f32_e32 v10, 0xbfb8aa3b, v6
	v_mul_f32_e32 v11, 0xbfb8aa3b, v7
	v_exp_f32_e32 v10, v10
	v_exp_f32_e32 v11, v11
	v_pk_mul_f32 v[4:5], v[14:15], v[4:5]
	v_pk_mul_f32 v[2:3], v[16:17], v[2:3]
	v_add_f32_e32 v10, 1.0, v10
	v_add_f32_e32 v11, 1.0, v11
	v_rcp_f32_e32 v10, v10
	v_rcp_f32_e32 v11, v11
	s_nop 0
	v_pk_mul_f32 v[6:7], v[10:11], v[6:7]
	s_nop 0
	v_pk_mul_f32 v[4:5], v[4:5], v[6:7]
	v_lshlrev_b32_e32 v6, 16, v13
	v_cvt_pk_bf16_f32 v4, v4, v5
	v_mul_f32_e32 v5, 0xbfb8aa3b, v6
	v_exp_f32_e32 v5, v5
	v_and_b32_e32 v7, 0xffff0000, v13
	v_add_f32_e32 v5, 1.0, v5
	v_rcp_f32_e32 v10, v5
	v_mul_f32_e32 v5, 0xbfb8aa3b, v7
	v_exp_f32_e32 v5, v5
	s_nop 0
	v_add_f32_e32 v5, 1.0, v5
	v_rcp_f32_e32 v11, v5
	s_nop 0
	v_pk_mul_f32 v[6:7], v[10:11], v[6:7]
	s_nop 0
	v_pk_mul_f32 v[2:3], v[2:3], v[6:7]
	s_nop 0
	v_cvt_pk_bf16_f32 v5, v2, v3
	global_store_dwordx2 v[8:9], v[4:5], off offset:224
	s_barrier
	s_cbranch_scc1 .LBB0_174
	v_readlane_b32 s96, v255, 10
	v_readlane_b32 s97, v255, 11
	v_readlane_b32 s74, v255, 8
	v_readlane_b32 s2, v255, 13
	v_readlane_b32 s75, v255, 9
	v_readlane_b32 s97, v255, 12
	v_readlane_b32 s93, v255, 19
